# lat-B loop: second V^T fragment pair of the first key sub-block read directly into dead registers, six v_mov shuffles per tile removed
# baseline (speedup 1.0000x reference)
.LBB0_210:
	v_sub_f32_e32 v4, v96, v1
	v_exp_f32_e32 v4, v4
	v_sub_f32_e32 v6, v97, v1
	v_exp_f32_e32 v6, v6
	v_sub_f32_e32 v7, v98, v1
	v_exp_f32_e32 v7, v7
	v_sub_f32_e32 v8, v99, v1
	v_exp_f32_e32 v8, v8
	v_add_f32_e32 v5, v6, v4
	v_add_f32_e32 v5, v7, v5
	v_add_f32_e32 v5, v8, v5
	v_cvt_pk_bf16_f32 v97, v7, v8
	v_sub_f32_e32 v8, v80, v205
	v_exp_f32_e32 v224, v8
	v_sub_f32_e32 v8, v81, v205
	v_exp_f32_e32 v226, v8
	v_sub_f32_e32 v8, v82, v205
	v_exp_f32_e32 v227, v8
	v_sub_f32_e32 v8, v83, v205
	v_exp_f32_e32 v228, v8
	v_sub_f32_e32 v8, v84, v205
	v_exp_f32_e32 v229, v8
	v_sub_f32_e32 v8, v85, v205
	v_exp_f32_e32 v230, v8
	v_sub_f32_e32 v8, v86, v205
	v_exp_f32_e32 v231, v8
	v_sub_f32_e32 v8, v87, v205
	v_exp_f32_e32 v232, v8
	v_sub_f32_e32 v8, v88, v205
	v_exp_f32_e32 v233, v8
	v_sub_f32_e32 v8, v89, v205
	v_add3_u32 v219, v219, v209, v160
	v_exp_f32_e32 v234, v8
	v_sub_f32_e32 v8, v90, v205
	v_lshl_add_u32 v84, v211, 1, v219
	v_lshl_add_u32 v88, v210, 1, v219
	v_exp_f32_e32 v235, v8
	v_sub_f32_e32 v8, v91, v205
	ds_read_b64 v[238:239], v84 offset:8192
	ds_read_b64 v[242:243], v84 offset:12288
	ds_read_b64 v[240:241], v88 offset:8192
	ds_read_b64 v[244:245], v88 offset:12288
	v_exp_f32_e32 v236, v8
	v_sub_f32_e32 v8, v92, v205
	v_sub_f32_e32 v9, v100, v1
	v_sub_f32_e32 v96, v103, v1
	v_exp_f32_e32 v237, v8
	v_sub_f32_e32 v8, v93, v205
	v_exp_f32_e32 v9, v9
	v_sub_f32_e32 v10, v101, v1
	v_exp_f32_e32 v99, v96
	v_sub_f32_e32 v96, v104, v1
	v_exp_f32_e32 v222, v8
	v_sub_f32_e32 v8, v94, v205
	v_exp_f32_e32 v10, v10
	v_sub_f32_e32 v11, v102, v1
	v_exp_f32_e32 v100, v96
	v_sub_f32_e32 v96, v105, v1
	v_exp_f32_e32 v223, v8
	v_sub_f32_e32 v8, v95, v205
	s_waitcnt lgkmcnt(0)
	v_exp_f32_e32 v11, v11
	v_exp_f32_e32 v101, v96
	v_sub_f32_e32 v96, v106, v1
	v_exp_f32_e32 v102, v96
	v_sub_f32_e32 v96, v107, v1
	v_add_f32_e32 v5, v9, v5
	v_exp_f32_e32 v103, v96
	v_sub_f32_e32 v96, v108, v1
	v_add_f32_e32 v5, v10, v5
	v_exp_f32_e32 v104, v96
	v_sub_f32_e32 v96, v109, v1
	v_cvt_pk_bf16_f32 v80, v224, v226
	v_cvt_pk_bf16_f32 v81, v227, v228
	v_cvt_pk_bf16_f32 v82, v229, v230
	v_cvt_pk_bf16_f32 v83, v231, v232
	v_add_f32_e32 v5, v11, v5
	v_exp_f32_e32 v105, v96
	v_sub_f32_e32 v96, v110, v1
	v_mfma_f32_32x32x16_bf16 v[32:47], v[238:241], v[80:83], v[32:47]
	v_lshl_add_u32 v84, v206, 1, v219
	v_add_f32_e32 v5, v99, v5
	v_exp_f32_e32 v106, v96
	v_sub_f32_e32 v96, v111, v1
	ds_read_b64 v[248:249], v84 offset:8192
	ds_read_b64 v[94:95], v84 offset:12288
	v_add_f32_e32 v5, v100, v5
	v_exp_f32_e32 v107, v96
	v_mfma_f32_32x32x16_bf16 v[16:31], v[242:245], v[80:83], v[16:31]
	v_lshl_add_u32 v80, v207, 1, v219
	ds_read_b64 v[246:247], v80 offset:8192
	ds_read_b64 v[92:93], v80 offset:12288
	v_cvt_pk_bf16_f32 v96, v4, v6
	v_cvt_pk_bf16_f32 v98, v9, v10
	v_cvt_pk_bf16_f32 v99, v11, v99
	v_add_f32_e32 v5, v101, v5
	v_add_f32_e32 v5, v102, v5
	v_mfma_f32_32x32x16_bf16 v[64:79], v[238:241], v[96:99], v[64:79]
	v_add_f32_e32 v5, v103, v5
	v_add_f32_e32 v5, v104, v5
	v_add_f32_e32 v5, v105, v5
	v_add_f32_e32 v5, v106, v5
	v_add_f32_e32 v5, v107, v5
	v_add_f32_e32 v3, v3, v5
	v_cvt_pk_bf16_f32 v4, v100, v101
	v_mfma_f32_32x32x16_bf16 v[48:63], v[242:245], v[96:99], v[48:63]
	s_waitcnt lgkmcnt(0)
	v_cvt_pk_bf16_f32 v5, v102, v103
	v_cvt_pk_bf16_f32 v6, v104, v105
	v_cvt_pk_bf16_f32 v7, v106, v107
	v_exp_f32_e32 v225, v8
	v_cvt_pk_bf16_f32 v8, v233, v234
	v_mfma_f32_32x32x16_bf16 v[64:79], v[246:249], v[4:7], v[64:79]
	v_cvt_pk_bf16_f32 v9, v235, v236
	v_cvt_pk_bf16_f32 v10, v237, v222
	v_cvt_pk_bf16_f32 v11, v223, v225
	v_mfma_f32_32x32x16_bf16 v[48:63], v[92:95], v[4:7], v[48:63]
	ds_read_b128 v[4:7], v220 offset:4096
	v_mfma_f32_32x32x16_bf16 v[32:47], v[246:249], v[8:11], v[32:47]
	v_mfma_f32_32x32x16_bf16 v[16:31], v[92:95], v[8:11], v[16:31]
	s_waitcnt lgkmcnt(0)
	v_mfma_f32_32x32x16_bf16 v[96:111], v[4:7], v[152:155], 0
	v_mfma_f32_32x32x16_bf16 v[80:95], v[4:7], v[156:159], 0
	ds_read_b128 v[4:7], v14 offset:4096
	s_waitcnt lgkmcnt(0)
	v_mfma_f32_32x32x16_bf16 v[96:111], v[4:7], v[140:143], v[96:111]
	v_mfma_f32_32x32x16_bf16 v[80:95], v[4:7], v[148:151], v[80:95]
	ds_read_b128 v[4:7], v221 offset:4096
	s_waitcnt lgkmcnt(0)
	v_mfma_f32_32x32x16_bf16 v[96:111], v[4:7], v[136:139], v[96:111]
	v_mfma_f32_32x32x16_bf16 v[80:95], v[4:7], v[144:147], v[80:95]
	ds_read_b128 v[4:7], v13 offset:4096
	s_waitcnt lgkmcnt(0)
	v_mfma_f32_32x32x16_bf16 v[96:111], v[4:7], v[124:127], v[96:111]
	v_mfma_f32_32x32x16_bf16 v[80:95], v[4:7], v[132:135], v[80:95]
	ds_read_b128 v[4:7], v15 offset:18432
	s_waitcnt lgkmcnt(0)
	v_mfma_f32_32x32x16_bf16 v[96:111], v[4:7], v[120:123], v[96:111]
	v_mfma_f32_32x32x16_bf16 v[80:95], v[4:7], v[128:131], v[80:95]
	ds_read_b128 v[4:7], v12 offset:18432
	s_waitcnt lgkmcnt(0)
	v_mfma_f32_32x32x16_bf16 v[96:111], v[4:7], v[112:115], v[96:111]
	v_mfma_f32_32x32x16_bf16 v[80:95], v[4:7], v[116:119], v[80:95]
	s_nop 10
	v_max_f32_e32 v4, v97, v97
	v_max_f32_e32 v5, v96, v96
	v_max_f32_e32 v4, v5, v4
	v_max3_f32 v4, v4, v98, v99
	v_max3_f32 v4, v4, v100, v101
	v_max3_f32 v4, v4, v102, v103
	v_max3_f32 v4, v4, v104, v105
	v_max3_f32 v4, v4, v106, v107
	v_max3_f32 v4, v4, v108, v109
	v_max3_f32 v4, v4, v110, v111
	v_mov_b32_e32 v5, v4
	s_nop 1
	v_permlane32_swap_b32_e32 v5, v4
	s_nop 1
	s_waitcnt lgkmcnt(0)
	v_max_f32_e32 v5, v5, v5
	v_max_f32_e32 v4, v4, v5
	v_add_f32_e32 v5, 0x41000000, v1
	v_cmp_gt_f32_e32 vcc, v4, v5
	s_cbranch_vccz .LBB0_212
	v_max_f32_e32 v4, v4, v4
	v_max_f32_e32 v5, v1, v1
	v_max_f32_e32 v5, v5, v4
	v_sub_f32_e32 v1, v1, v5
	v_exp_f32_e32 v4, v1
	v_mov_b32_e32 v1, v5
	v_mul_f32_e32 v3, v3, v4
	v_pk_mul_f32 v[78:79], v[78:79], v[4:5] op_sel_hi:[1,0]
	v_pk_mul_f32 v[76:77], v[76:77], v[4:5] op_sel_hi:[1,0]
	v_pk_mul_f32 v[74:75], v[74:75], v[4:5] op_sel_hi:[1,0]
	v_pk_mul_f32 v[72:73], v[72:73], v[4:5] op_sel_hi:[1,0]
	v_pk_mul_f32 v[70:71], v[70:71], v[4:5] op_sel_hi:[1,0]
	v_pk_mul_f32 v[68:69], v[68:69], v[4:5] op_sel_hi:[1,0]
	v_pk_mul_f32 v[66:67], v[66:67], v[4:5] op_sel_hi:[1,0]
	v_pk_mul_f32 v[64:65], v[64:65], v[4:5] op_sel_hi:[1,0]
	v_pk_mul_f32 v[62:63], v[62:63], v[4:5] op_sel_hi:[1,0]
	v_pk_mul_f32 v[60:61], v[60:61], v[4:5] op_sel_hi:[1,0]
	v_pk_mul_f32 v[58:59], v[58:59], v[4:5] op_sel_hi:[1,0]
	v_pk_mul_f32 v[56:57], v[56:57], v[4:5] op_sel_hi:[1,0]
	v_pk_mul_f32 v[54:55], v[54:55], v[4:5] op_sel_hi:[1,0]
	v_pk_mul_f32 v[52:53], v[52:53], v[4:5] op_sel_hi:[1,0]
	v_pk_mul_f32 v[50:51], v[50:51], v[4:5] op_sel_hi:[1,0]
	v_pk_mul_f32 v[48:49], v[48:49], v[4:5] op_sel_hi:[1,0]
